# static priority raise for waves 4-7 (the younger half) through the attention phase, guide 7.4
# baseline (speedup 1.0000x reference)
; __device__ __forceinline__ void attn_unit(LAS unsigned char* lds, const bf16_t* Q, bf16_t* O, const bf16_t* Kb, const bf16_t* Vb, const float* sinks, int unit, int tid, int lane, int wid, int chain_ui) {
;     const int n = unit & 63, g = (unit >> 6) & 3, b = unit >> 8;
;     const int r0 = b * SEQ + n * 128;
;     const int q = lane & 31, hi = lane >> 5, hq = wid >> 1, head = 4 * g + hq;
;     bf16x8 Qf[2][4];
; #pragma unroll
;     for (int it = 0; it < 2; ++it) { const bf16_t* qp = Q + (size_t)(r0 + 32 * ((wid & 1) * 2 + it) + q) * DM + head * 64;
; #pragma unroll
;         for (int d0 = 0; d0 < 4; ++d0) Qf[it][d0] = *(const bf16x8*)(qp + 16 * d0 + 8 * hi); }
;     const bool full = chain_ui <= 0; const int par = full ? 0 : (chain_ui & 1);
;     const int ph0 = par * 128, ph1 = (par ^ 1) * 128;
;     u32x4 kk[4], vv[4];
; #pragma unroll
;     for (int i = 0; i < 4; ++i) { const int t_ = tid + 512 * (i & 1), krl = t_ >> 3, ch = t_ & 7, h = (i < 2) ? 1 : 0;
;         kk[i] = (u32x4){0u, 0u, 0u, 0u};
;         if (h == 1 || (full && n > 0)) kk[i] = *(const u32x4*)(Kb + (size_t)(r0 - 128 + h * 128 + krl) * 256 + g * 64 + ch * 8); }
; #pragma unroll
;     for (int i = 0; i < 4; ++i) { const int t_ = tid + 512 * (i & 1), kvl = t_ & 127, c = t_ >> 7, h = (i < 2) ? 1 : 0;
;         vv[i] = (u32x4){0u, 0u, 0u, 0u};
;         if (h == 1 || (full && n > 0)) vv[i] = *(const u32x4*)(Vb + (size_t)(r0 - 128 + h * 128 + kvl) * 256 + g * 64 + c * 8); }
; #pragma unroll
;     for (int i = 0; i < 4; ++i) { const int t_ = tid + 512 * (i & 1), krl = t_ >> 3, ch = t_ & 7, h = (i < 2) ? 1 : 0;
;         if (h == 1 || full) *(LAS u32x4*)(lds + KS_OFF + ((h ? ph1 : ph0) + krl) * KS_PITCH + ch * 16) = kk[i]; }
; #pragma unroll
;     for (int i = 0; i < 4; ++i) { const int t_ = tid + 512 * (i & 1), kvl = t_ & 127, c = t_ >> 7, h = (i < 2) ? 1 : 0;
;         if (h == 1 || full) { LAS bf16_t* vp = (LAS bf16_t*)(lds + VS_OFF + (c * 8) * VS_PITCH + ((h ? ph1 : ph0) + kvl) * 2);
; #pragma unroll
;             for (int e = 0; e < 8; ++e) { const unsigned w = vv[i][e >> 1]; vp[e * (VS_PITCH / 2)] = (bf16_t)((e & 1) ? (w >> 16) : (w & 0xffffu)); } } }
;     __syncthreads();
;     const int ks = (q & 0x13) | ((q & 4) << 1) | ((q & 8) >> 1);
;     const float sink = sinks[head];
; #pragma unroll
;     for (int it = 0; it < 2; ++it) {
;         const int rb = (wid & 1) * 2 + it;
.LBB0_636:
	s_cmpk_gt_i32 s11, 0x3ff
	s_cbranch_scc1 .LBB0_653
	v_writelane_b32 v254, s36, 17
	s_add_u32 s25, s78, 0xc000000
	s_addc_u32 s0, s79, 0
	v_writelane_b32 v254, s37, 18
	v_writelane_b32 v254, s0, 13
	s_add_u32 s0, s78, 0x1d000000
	v_writelane_b32 v254, s0, 15
	s_addc_u32 s0, s79, 0
	v_writelane_b32 v254, s0, 19
	v_lshlrev_b32_e32 v2, 4, v78
	v_readlane_b32 s0, v254, 0
	s_lshr_b32 s0, s0, 7
	v_mov_b32_e32 v101, 0
	v_writelane_b32 v254, s0, 0
	v_and_b32_e32 v100, 0x70, v2
	v_readlane_b32 s2, v254, 7
	s_nop 1
	s_cmp_ge_u32 s2, 4
	s_cbranch_scc0 .Lattn_prio_done
	s_setprio 1
.Lattn_prio_done:
	s_lshl_b32 s0, s2, 1
	s_and_b32 s4, s0, 2
	v_lshl_add_u64 v[2:3], s[78:79], 0, v[100:101]
	s_mov_b64 s[0:1], 0x1c000000
	v_lshl_add_u64 v[102:103], v[2:3], 0, s[0:1]
	v_add_u32_e32 v2, 0x200, v78
	v_ashrrev_i32_e32 v3, 4, v78
	v_ashrrev_i32_e32 v109, 3, v2
	v_and_b32_e32 v104, -8, v3
	v_ashrrev_i32_e32 v2, 4, v2
	s_movk_i32 s0, 0x210
	v_and_b32_e32 v106, -8, v2
	v_mul_lo_u32 v2, v104, s0
	v_add_u32_e32 v124, 0, v2
	v_mul_lo_u32 v2, v106, s0
	v_lshlrev_b32_e32 v6, 1, v79
	v_lshrrev_b32_e32 v7, 1, v78
	v_add_u32_e32 v125, 0, v2
	v_and_b32_e32 v2, 19, v78
	v_and_b32_e32 v6, 8, v6
	v_and_b32_e32 v7, 4, v7
	v_or3_b32 v127, v7, v2, v6
	v_mbcnt_lo_u32_b32 v2, -1, 0
	v_mbcnt_hi_u32_b32 v2, -1, v2
	v_and_b32_e32 v8, 64, v2
	v_xor_b32_e32 v7, 32, v2
	v_add_u32_e32 v8, 64, v8
	v_cmp_lt_i32_e32 vcc, v7, v8
	v_and_b32_e32 v1, 31, v78
	v_mad_u32_u24 v131, v1, s0, 0
	v_cndmask_b32_e32 v2, v2, v7, vcc
	v_lshlrev_b32_e32 v130, 2, v2
	v_or_b32_e32 v2, 32, v79
	v_mad_u32_u24 v132, v2, s0, 0
	s_mul_i32 s0, s2, 0x1200
	s_add_i32 s0, s0, 0
	s_add_i32 s0, s0, 0x11400
	s_movk_i32 s15, 0x90
	v_mov_b32_e32 v2, s0
	v_mad_u32_u24 v7, v1, s15, v2
	v_and_b32_e32 v2, 7, v78
	s_lshl_b32 s5, s4, 5
	v_lshl_add_u32 v9, v2, 4, s0
	s_lshl_b32 s0, s4, 6
	v_lshrrev_b32_e32 v4, 5, v79
	v_or_b32_e32 v6, 0x80, v1
	v_writelane_b32 v254, s0, 20
	s_add_i32 s0, s5, 0x60
	s_movk_i32 s1, 0x80
	s_and_b32 s0, s0, 0x60
	v_mad_i32_i24 v10, v4, -8, v6
	v_writelane_b32 v254, s0, 21
	v_cmp_gt_u32_e64 s[2:3], s1, v10
	v_mad_i32_i24 v10, v4, -8, -1
	v_add_u32_e32 v12, v10, v6
	v_writelane_b32 v254, s2, 22
	v_lshlrev_b32_e32 v98, 3, v4
	v_lshlrev_b32_e32 v128, 4, v4
	v_writelane_b32 v254, s3, 23
	v_cmp_gt_u32_e64 s[2:3], s1, v12
	v_mad_i32_i24 v12, v4, -8, -2
	v_add_u32_e32 v13, v12, v6
	v_writelane_b32 v254, s2, 24
	s_or_b32 s14, s5, 32
	v_lshrrev_b32_e32 v8, 3, v79
	v_writelane_b32 v254, s3, 25
	v_cmp_gt_u32_e64 s[2:3], s1, v13
	v_mad_i32_i24 v13, v4, -8, -3
	v_add_u32_e32 v14, v13, v6
	v_writelane_b32 v254, s2, 26
	v_ashrrev_i32_e32 v99, 3, v78
	v_add_u32_e32 v108, 0, v100
	v_writelane_b32 v254, s3, 27
	v_cmp_gt_u32_e64 s[2:3], s1, v14
	v_mad_i32_i24 v14, v4, -8, -4
	v_add_u32_e32 v15, v14, v6
	v_writelane_b32 v254, s2, 28
	v_mul_lo_u32 v3, v99, s15
	v_mul_lo_u32 v5, v109, s15
	v_writelane_b32 v254, s3, 29
	v_cmp_gt_u32_e64 s[2:3], s1, v15
	v_mad_i32_i24 v15, v4, -8, -5
	v_add_u32_e32 v16, v15, v6
	v_writelane_b32 v254, s2, 30
	v_and_b32_e32 v123, 0x7f, v78
	v_lshlrev_b32_e32 v2, 3, v2
	v_writelane_b32 v254, s3, 31
	v_cmp_gt_u32_e64 s[2:3], s1, v16
	v_mad_i32_i24 v16, v4, -8, -6
	v_add_u32_e32 v17, v16, v6
	v_writelane_b32 v254, s2, 32
	v_mul_u32_u24_e32 v11, 0x90, v8
	v_or_b32_e32 v122, 0xffffff80, v78
	v_writelane_b32 v254, s3, 33
	v_cmp_gt_u32_e64 s[2:3], s1, v17
	v_mad_i32_i24 v17, v4, -8, -7
	v_add_u32_e32 v18, v17, v6
	v_writelane_b32 v254, s2, 34
	v_ashrrev_i32_e32 v105, 31, v104
	v_ashrrev_i32_e32 v107, 31, v106
	v_writelane_b32 v254, s3, 35
	v_cmp_gt_u32_e64 s[2:3], s1, v18
	v_mad_i32_i24 v18, v4, -8, -16
	v_add_u32_e32 v19, v18, v6
	v_writelane_b32 v254, s2, 36
	s_mov_b32 s9, 0
	v_lshlrev_b32_e32 v126, 1, v123
	v_writelane_b32 v254, s3, 37
	v_cmp_gt_u32_e64 s[2:3], s1, v19
	v_not_b32_e32 v19, 16
	v_mad_i32_i24 v19, v4, -8, v19
	v_writelane_b32 v254, s2, 38
	v_add_u32_e32 v20, v19, v6
	v_add_u32_e32 v129, 0, v128
	v_writelane_b32 v254, s3, 39
	v_cmp_gt_u32_e64 s[2:3], s1, v20
	v_not_b32_e32 v20, 17
	v_mad_i32_i24 v20, v4, -8, v20
	v_writelane_b32 v254, s2, 40
	v_add_u32_e32 v21, v20, v6
	v_add_u32_e32 v133, v108, v3
	v_writelane_b32 v254, s3, 41
	v_cmp_gt_u32_e64 s[2:3], s1, v21
	v_not_b32_e32 v21, 18
	v_mad_i32_i24 v21, v4, -8, v21
	v_writelane_b32 v254, s2, 42
	v_add_u32_e32 v22, v21, v6
	v_add_u32_e32 v134, v108, v5
	v_writelane_b32 v254, s3, 43
	v_cmp_gt_u32_e64 s[2:3], s1, v22
	v_not_b32_e32 v22, 19
	v_mad_i32_i24 v22, v4, -8, v22
	v_add_u32_e32 v23, v22, v6
	v_cmp_gt_u32_e64 s[26:27], s1, v23
	v_not_b32_e32 v23, 20
	v_mad_i32_i24 v23, v4, -8, v23
	v_add_u32_e32 v24, v23, v6
	v_cmp_gt_u32_e64 s[28:29], s1, v24
	v_not_b32_e32 v24, 21
	v_mad_i32_i24 v24, v4, -8, v24
	v_add_u32_e32 v25, v24, v6
	v_cmp_gt_u32_e64 s[30:31], s1, v25
	v_not_b32_e32 v25, 22
	v_mad_i32_i24 v25, v4, -8, v25
	v_mad_i32_i24 v4, v4, -8, v1
	v_cmp_lt_i32_e64 s[36:37], -1, v4
	v_add_u32_e32 v4, v10, v1
	v_cmp_lt_i32_e64 s[38:39], -1, v4
	v_add_u32_e32 v4, v12, v1
	v_cmp_lt_i32_e64 s[40:41], -1, v4
	v_add_u32_e32 v4, v13, v1
	v_cmp_lt_i32_e64 s[42:43], -1, v4
	v_add_u32_e32 v4, v14, v1
	v_cmp_lt_i32_e64 s[44:45], -1, v4
	v_add_u32_e32 v4, v15, v1
	v_cmp_lt_i32_e64 s[46:47], -1, v4
	v_add_u32_e32 v4, v16, v1
	v_cmp_lt_i32_e64 s[48:49], -1, v4
	v_add_u32_e32 v4, v17, v1
	v_cmp_lt_i32_e64 s[50:51], -1, v4
	v_add_u32_e32 v4, v18, v1
	v_cmp_lt_i32_e64 s[52:53], -1, v4
	v_add_u32_e32 v4, v19, v1
	v_cmp_lt_i32_e64 s[54:55], -1, v4
	v_add_u32_e32 v4, v20, v1
	v_cmp_lt_i32_e64 s[56:57], -1, v4
	v_add_u32_e32 v4, v21, v1
	v_cmp_lt_i32_e64 s[58:59], -1, v4
	v_add_u32_e32 v4, v22, v1
	v_cmp_lt_i32_e64 s[60:61], -1, v4
	v_add_u32_e32 v4, v23, v1
	v_cmp_lt_i32_e64 s[62:63], -1, v4
	v_add_u32_e32 v4, v24, v1
	v_add_u32_e32 v6, v25, v6
	v_cmp_lt_i32_e64 s[64:65], -1, v4
	v_add_u32_e32 v4, v25, v1
	v_cmp_gt_u32_e64 s[34:35], s1, v6
	v_cmp_lt_i32_e64 s[66:67], -1, v4
	v_lshlrev_b32_e32 v4, 10, v8
	v_or_b32_e32 v6, 8, v8
	s_and_b64 s[0:1], exec, s[6:7]
	v_mul_u32_u24_e32 v12, 0x90, v6
	v_lshlrev_b32_e32 v6, 10, v6
	v_or_b32_e32 v8, 0x4000, v4
	v_or_b32_e32 v10, 0x6000, v4
	s_cselect_b32 s16, s33, 1
	v_writelane_b32 v254, s2, 44
	s_lshl_b32 s17, s11, 5
	s_lshl_b32 s18, s16, 5
	v_lshlrev_b32_e32 v110, 1, v2
	s_mov_b32 s19, 0xff61b1e6
	v_add_u32_e32 v135, v7, v98
	v_add_u32_e32 v136, v9, v11
	v_lshlrev_b32_e32 v112, 1, v4
	v_add_u32_e32 v137, v9, v12
	v_lshlrev_b32_e32 v114, 1, v6
	v_lshlrev_b32_e32 v116, 1, v8
	v_lshlrev_b32_e32 v118, 1, v10
	v_mov_b32_e32 v138, 0xf149f2ca
	s_mov_b32 s20, 0
	s_mov_b32 s10, 0x3fb8aa3b
	v_writelane_b32 v254, s3, 45
	s_branch .LBB0_639

;     __host__ __device__ void init(int M, int N, int G_, int c_) { b.init(M, N, G_, c_); }
; #define SEAM(k) do { if (IN(k) && IN((k) + 1)) xcd_barrier(bar); } while (0)
; __global__ void __launch_bounds__(512, 2) mk_fwd(Args A) {
;     ...
;         for (int ui = 0, u = xmap ? 4 * vcu : cid; u < BATCH * 4 * (SEQ / 128) && (!xmap || ui < 4); ++ui, u += xmap ? 1 : G) attn_unit(lds, (const bf16_t*)(ws + WS_Q), (bf16_t*)(ws + WS_Q), (const bf16_t*)(ws + WS_K), (const bf16_t*)(ws + WS_V), A.sinks, u, t5, l5, wave, xmap ? ui : 0); } SEAM(5);
;     if (IN(6)) { pg8::Gemm g{(const bf16_t*)(ws + WS_BG), (const bf16_t*)(ws + WS_WC), M, DM, DM, (const bf16_t*)(ws + WS_Q), (const bf16_t*)(ws + WS_WA)}; pg8::DualOrder S; S.init(M, DM, G, cid);
.LBB0_652:
	s_setprio 0
	v_readlane_b32 s0, v254, 1
	v_readlane_b32 s1, v254, 2
	s_load_dwordx4 s[76:79], s[0:1], 0x90
	v_readlane_b32 s48, v254, 8
	v_readlane_b32 s36, v254, 17
	v_readlane_b32 s49, v254, 9
	v_readlane_b32 s50, v254, 10
	v_readlane_b32 s51, v254, 11
	v_readlane_b32 s37, v254, 18
